# LRU pass2 conv: hoist 64 sequential token loads into two 32-deep prefetch blocks (was 16 serialized batches of 4)
# speedup vs baseline: 1.0112x; 1.0006x over previous
; DI u16 f2bf(float f) { return (u16)(pack2(f, 0.f) & 0xffffu); }
; DI float bf2f(u16 h) { return __uint_as_float(((uint32_t)h) << 16); }
; template <bool FINAL>
; DI void lru_item(int ws, PP p, char* shm, int item) {
;     ...
;   {
;     const int ch = wid * 64 + lane;
;     const float w0 = p->conv_w[ch], w1 = p->conv_w[512 + ch], w2 = p->conv_w[1024 + ch], w3 = p->conv_w[1536 + ch], cb = p->conv_b[ch];
;     const u16* up = u + ((long)b * SEQ + t0) * IN0 + ch;
;     float xm3 = 0.f, xm2 = 0.f, xm1 = 0.f;
;     if (t0 > 0) { xm3 = bf2f(up[-3 * IN0]); xm2 = bf2f(up[-2 * IN0]); xm1 = bf2f(up[-1 * IN0]); }
;     for (int t = 0; t < 64; ++t) {
;       float xv = bf2f(up[(long)t * IN0]);
;       float xc = w0 * xm3 + w1 * xm2 + w2 * xm1 + w3 * xv + cb;
;       XC[t * KVS + lane] = f2bf(xc);
;       xm3 = xm2; xm2 = xm1; xm1 = xv;
;     }
;   }
.LBB0_673:
	s_mov_b32 s98, 0x1400
	s_mov_b32 s99, 0
	global_load_ushort v142, v[12:13], off
	v_lshl_add_u64 v[228:229], v[12:13], 0, s[98:99]
	global_load_ushort v143, v[228:229], off
	v_lshl_add_u64 v[228:229], v[228:229], 0, s[98:99]
	global_load_ushort v144, v[228:229], off
	v_lshl_add_u64 v[228:229], v[228:229], 0, s[98:99]
	global_load_ushort v145, v[228:229], off
	v_lshl_add_u64 v[228:229], v[228:229], 0, s[98:99]
	global_load_ushort v146, v[228:229], off
	v_lshl_add_u64 v[228:229], v[228:229], 0, s[98:99]
	global_load_ushort v147, v[228:229], off
	v_lshl_add_u64 v[228:229], v[228:229], 0, s[98:99]
	global_load_ushort v148, v[228:229], off
	v_lshl_add_u64 v[228:229], v[228:229], 0, s[98:99]
	global_load_ushort v149, v[228:229], off
	v_lshl_add_u64 v[228:229], v[228:229], 0, s[98:99]
	global_load_ushort v150, v[228:229], off
	v_lshl_add_u64 v[228:229], v[228:229], 0, s[98:99]
	global_load_ushort v151, v[228:229], off
	v_lshl_add_u64 v[228:229], v[228:229], 0, s[98:99]
	global_load_ushort v152, v[228:229], off
	v_lshl_add_u64 v[228:229], v[228:229], 0, s[98:99]
	global_load_ushort v153, v[228:229], off
	v_lshl_add_u64 v[228:229], v[228:229], 0, s[98:99]
	global_load_ushort v154, v[228:229], off
	v_lshl_add_u64 v[228:229], v[228:229], 0, s[98:99]
	global_load_ushort v155, v[228:229], off
	v_lshl_add_u64 v[228:229], v[228:229], 0, s[98:99]
	global_load_ushort v156, v[228:229], off
	v_lshl_add_u64 v[228:229], v[228:229], 0, s[98:99]
	global_load_ushort v157, v[228:229], off
	v_lshl_add_u64 v[228:229], v[228:229], 0, s[98:99]
	global_load_ushort v158, v[228:229], off
	v_lshl_add_u64 v[228:229], v[228:229], 0, s[98:99]
	global_load_ushort v159, v[228:229], off
	v_lshl_add_u64 v[228:229], v[228:229], 0, s[98:99]
	global_load_ushort v160, v[228:229], off
	v_lshl_add_u64 v[228:229], v[228:229], 0, s[98:99]
	global_load_ushort v161, v[228:229], off
	v_lshl_add_u64 v[228:229], v[228:229], 0, s[98:99]
	global_load_ushort v162, v[228:229], off
	v_lshl_add_u64 v[228:229], v[228:229], 0, s[98:99]
	global_load_ushort v163, v[228:229], off
	v_lshl_add_u64 v[228:229], v[228:229], 0, s[98:99]
	global_load_ushort v164, v[228:229], off
	v_lshl_add_u64 v[228:229], v[228:229], 0, s[98:99]
	global_load_ushort v165, v[228:229], off
	v_lshl_add_u64 v[228:229], v[228:229], 0, s[98:99]
	global_load_ushort v166, v[228:229], off
	v_lshl_add_u64 v[228:229], v[228:229], 0, s[98:99]
	global_load_ushort v167, v[228:229], off
	v_lshl_add_u64 v[228:229], v[228:229], 0, s[98:99]
	global_load_ushort v168, v[228:229], off
	v_lshl_add_u64 v[228:229], v[228:229], 0, s[98:99]
	global_load_ushort v169, v[228:229], off
	v_lshl_add_u64 v[228:229], v[228:229], 0, s[98:99]
	global_load_ushort v170, v[228:229], off
	v_lshl_add_u64 v[228:229], v[228:229], 0, s[98:99]
	global_load_ushort v171, v[228:229], off
	v_lshl_add_u64 v[228:229], v[228:229], 0, s[98:99]
	global_load_ushort v172, v[228:229], off
	v_lshl_add_u64 v[228:229], v[228:229], 0, s[98:99]
	global_load_ushort v173, v[228:229], off
	s_waitcnt vmcnt(0)
	v_ashrrev_i32_e32 v10, 6, v14
	v_and_b32_e32 v5, 63, v14
	v_and_b32_e32 v84, 31, v14
	v_bfe_u32 v7, v14, 5, 1
	v_and_b32_e32 v85, 0xffffffc0, v14
	v_add_co_u32_e32 v14, vcc, 0x2000, v12
	s_movk_i32 s3, 0x2400
	s_nop 0
	v_addc_co_u32_e32 v15, vcc, 0, v13, vcc
	v_mov_b32_e32 v17, v144
	v_add_co_u32_e32 v14, vcc, 0x3000, v12
	v_mul_lo_u32 v9, v10, s3
	s_nop 0
	v_addc_co_u32_e32 v15, vcc, 0, v13, vcc
	v_mov_b32_e32 v18, v145
	v_add_co_u32_e32 v14, vcc, s51, v12
	v_lshl_or_b32 v11, v5, 1, v9
	s_nop 0
	v_addc_co_u32_e32 v15, vcc, 0, v13, vcc
	v_mov_b32_e32 v14, v143
	s_nop 0
	v_mov_b32_e32 v20, v142
	s_movk_i32 s3, 0x7000
	s_and_b32 s89, s0, 7
	s_addk_i32 s1, 0xff88
	v_lshlrev_b32_e32 v64, 4, v7
	s_mov_b32 s35, s23
	s_mov_b32 s22, 0
	v_lshlrev_b32_e32 v86, 2, v7
	v_cmp_gt_u32_e64 s[10:11], 32, v5
	v_mad_u32_u24 v87, v7, s84, v9
	s_mov_b64 s[48:49], -1
	s_waitcnt vmcnt(2)
	v_lshlrev_b32_e32 v19, 16, v18
	v_lshlrev_b32_e32 v18, 16, v17
	s_waitcnt vmcnt(1)
	v_lshlrev_b32_e32 v15, 16, v14
	s_waitcnt vmcnt(0)
	v_lshlrev_b32_e32 v14, 16, v20
	v_pk_mov_b32 v[22:23], v[2:3], v[14:15] op_sel:[1,0]
	v_pk_mov_b32 v[20:21], v[14:15], v[18:19] op_sel:[1,0]
	v_mov_b32_e32 v17, v22
	v_pk_mov_b32 v[24:25], v[0:1], v[16:17] op_sel:[1,0]
	v_pk_mov_b32 v[26:27], v[22:23], v[20:21] op_sel:[1,0]
	v_pk_mul_f32 v[16:17], v[8:9], v[16:17] op_sel_hi:[0,1]
	v_pk_mul_f32 v[26:27], v[8:9], v[26:27] op_sel_hi:[0,1]
	v_pk_fma_f32 v[16:17], v[4:5], v[24:25], v[16:17] op_sel_hi:[0,1,1]
	v_pk_fma_f32 v[24:25], v[4:5], v[22:23], v[26:27] op_sel_hi:[0,1,1]
	v_pk_fma_f32 v[16:17], v[6:7], v[22:23], v[16:17] op_sel_hi:[0,1,1]
	v_pk_fma_f32 v[24:25], v[6:7], v[20:21], v[24:25] op_sel_hi:[0,1,1]
	v_pk_fma_f32 v[14:15], v[0:1], v[14:15], v[16:17] op_sel_hi:[0,1,1]
	v_pk_fma_f32 v[22:23], v[0:1], v[18:19], v[24:25] op_sel_hi:[0,1,1]
	v_pk_add_f32 v[14:15], v[2:3], v[14:15] op_sel_hi:[0,1]
	v_pk_add_f32 v[16:17], v[2:3], v[22:23] op_sel_hi:[0,1]
	v_cvt_pk_bf16_f32 v14, v14, s0
	v_cvt_pk_bf16_f32 v1, v17, s0
	v_cvt_pk_bf16_f32 v3, v16, s0
	v_cvt_pk_bf16_f32 v15, v15, s0
	ds_write_b16 v11, v14
	ds_write_b16 v11, v15 offset:144
	ds_write_b16 v11, v3 offset:288
	ds_write_b16 v11, v1 offset:432
	v_add_co_u32_e32 v14, vcc, s3, v12
	s_mov_b32 s3, 0x8000
	s_nop 0
	v_addc_co_u32_e32 v15, vcc, 0, v13, vcc
	v_mov_b32_e32 v1, v148
	v_add_co_u32_e32 v14, vcc, s3, v12
	s_movk_i32 s3, 0x5000
	s_nop 0
	v_addc_co_u32_e32 v15, vcc, 0, v13, vcc
	v_mov_b32_e32 v3, v149
	v_add_co_u32_e32 v14, vcc, s3, v12
	s_movk_i32 s3, 0x6000
	s_nop 0
	v_addc_co_u32_e32 v15, vcc, 0, v13, vcc
	v_mov_b32_e32 v16, v146
	v_add_co_u32_e32 v14, vcc, s3, v12
	s_mov_b32 s3, 0xc000
	s_nop 0
	v_addc_co_u32_e32 v15, vcc, 0, v13, vcc
	v_mov_b32_e32 v14, v147
	s_waitcnt vmcnt(3)
; DI u16 f2bf(float f) { return (u16)(pack2(f, 0.f) & 0xffffu); }
; DI float bf2f(u16 h) { return __uint_as_float(((uint32_t)h) << 16); }
; template <bool FINAL>
; DI void lru_item(int ws, PP p, char* shm, int item) {
;     ...
;     for (int t = 0; t < 64; ++t) {
;       float xv = bf2f(up[(long)t * IN0]);
;       float xc = w0 * xm3 + w1 * xm2 + w2 * xm1 + w3 * xv + cb;
;       XC[t * KVS + lane] = f2bf(xc);
;       xm3 = xm2; xm2 = xm1; xm1 = xv;
;     }
	v_lshlrev_b32_e32 v22, 16, v1
	s_waitcnt vmcnt(2)
	v_lshlrev_b32_e32 v23, 16, v3
	s_waitcnt vmcnt(0)
	v_lshlrev_b32_e32 v15, 16, v14
	v_lshlrev_b32_e32 v14, 16, v16
	v_pk_mov_b32 v[16:17], v[18:19], v[14:15] op_sel:[1,0]
	v_pk_mov_b32 v[24:25], v[14:15], v[22:23] op_sel:[1,0]
	v_pk_mov_b32 v[26:27], v[20:21], v[16:17] op_sel:[1,0]
	v_pk_mov_b32 v[18:19], v[16:17], v[24:25] op_sel:[1,0]
	v_pk_mul_f32 v[26:27], v[8:9], v[26:27] op_sel_hi:[0,1]
	v_pk_mul_f32 v[18:19], v[8:9], v[18:19] op_sel_hi:[0,1]
	v_pk_fma_f32 v[20:21], v[4:5], v[20:21], v[26:27] op_sel_hi:[0,1,1]
	v_pk_fma_f32 v[18:19], v[4:5], v[16:17], v[18:19] op_sel_hi:[0,1,1]
	v_pk_fma_f32 v[16:17], v[6:7], v[16:17], v[20:21] op_sel_hi:[0,1,1]
	v_pk_fma_f32 v[18:19], v[6:7], v[24:25], v[18:19] op_sel_hi:[0,1,1]
	v_pk_fma_f32 v[14:15], v[0:1], v[14:15], v[16:17] op_sel_hi:[0,1,1]
	v_pk_fma_f32 v[18:19], v[0:1], v[22:23], v[18:19] op_sel_hi:[0,1,1]
	v_pk_add_f32 v[14:15], v[2:3], v[14:15] op_sel_hi:[0,1]
	v_pk_add_f32 v[16:17], v[2:3], v[18:19] op_sel_hi:[0,1]
	v_cvt_pk_bf16_f32 v14, v14, s0
	v_cvt_pk_bf16_f32 v1, v17, s0
	v_cvt_pk_bf16_f32 v3, v16, s0
	v_cvt_pk_bf16_f32 v15, v15, s0
	ds_write_b16 v11, v14 offset:576
	ds_write_b16 v11, v15 offset:720
	ds_write_b16 v11, v3 offset:864
	ds_write_b16 v11, v1 offset:1008
	v_add_co_u32_e32 v14, vcc, s3, v12
	s_mov_b32 s3, 0xd000
	s_nop 0
	v_addc_co_u32_e32 v15, vcc, 0, v13, vcc
	v_mov_b32_e32 v1, v152
	v_add_co_u32_e32 v14, vcc, s3, v12
	s_mov_b32 s3, 0xa000
	s_nop 0
	v_addc_co_u32_e32 v15, vcc, 0, v13, vcc
	v_mov_b32_e32 v3, v153
	v_add_co_u32_e32 v14, vcc, s3, v12
	s_mov_b32 s3, 0xb000
	s_nop 0
	v_addc_co_u32_e32 v15, vcc, 0, v13, vcc
	v_mov_b32_e32 v16, v150
	v_add_co_u32_e32 v14, vcc, s3, v12
	s_mov_b32 s3, 0x11000
	s_nop 0
	v_addc_co_u32_e32 v15, vcc, 0, v13, vcc
	v_mov_b32_e32 v14, v151
	s_waitcnt vmcnt(2)
	v_lshlrev_b32_e32 v17, 16, v3
	s_waitcnt vmcnt(1)
	v_lshlrev_b32_e32 v18, 16, v16
	v_lshlrev_b32_e32 v16, 16, v1
	s_waitcnt vmcnt(0)
	v_lshlrev_b32_e32 v19, 16, v14
	v_pk_mov_b32 v[20:21], v[22:23], v[18:19] op_sel:[1,0]
	v_pk_mov_b32 v[14:15], v[18:19], v[16:17] op_sel:[1,0]
	v_pk_mov_b32 v[22:23], v[24:25], v[20:21] op_sel:[1,0]
	v_pk_mov_b32 v[26:27], v[20:21], v[14:15] op_sel:[1,0]
	v_pk_mul_f32 v[22:23], v[8:9], v[22:23] op_sel_hi:[0,1]
	v_pk_mul_f32 v[26:27], v[8:9], v[26:27] op_sel_hi:[0,1]
	v_pk_fma_f32 v[22:23], v[4:5], v[24:25], v[22:23] op_sel_hi:[0,1,1]
	v_pk_fma_f32 v[26:27], v[4:5], v[20:21], v[26:27] op_sel_hi:[0,1,1]
	v_pk_fma_f32 v[20:21], v[6:7], v[20:21], v[22:23] op_sel_hi:[0,1,1]
	v_pk_fma_f32 v[22:23], v[6:7], v[14:15], v[26:27] op_sel_hi:[0,1,1]
	v_pk_fma_f32 v[18:19], v[0:1], v[18:19], v[20:21] op_sel_hi:[0,1,1]
	v_pk_fma_f32 v[22:23], v[0:1], v[16:17], v[22:23] op_sel_hi:[0,1,1]
	v_pk_add_f32 v[18:19], v[2:3], v[18:19] op_sel_hi:[0,1]
	v_pk_add_f32 v[20:21], v[2:3], v[22:23] op_sel_hi:[0,1]
	v_cvt_pk_bf16_f32 v18, v18, s0
	v_cvt_pk_bf16_f32 v1, v21, s0
	v_cvt_pk_bf16_f32 v3, v20, s0
	v_cvt_pk_bf16_f32 v19, v19, s0
	ds_write_b16 v11, v18 offset:1152
	ds_write_b16 v11, v19 offset:1296
	ds_write_b16 v11, v3 offset:1440
	ds_write_b16 v11, v1 offset:1584
	v_add_co_u32_e32 v18, vcc, s3, v12
	s_mov_b32 s3, 0x12000
	s_nop 0
	v_addc_co_u32_e32 v19, vcc, 0, v13, vcc
	v_mov_b32_e32 v1, v156
	v_add_co_u32_e32 v18, vcc, s3, v12
	s_mov_b32 s3, 0xf000
	s_nop 0
	v_addc_co_u32_e32 v19, vcc, 0, v13, vcc
	v_mov_b32_e32 v3, v157
	v_add_co_u32_e32 v18, vcc, s3, v12
	s_mov_b32 s3, 0x10000
	s_nop 0
	v_addc_co_u32_e32 v19, vcc, 0, v13, vcc
	v_mov_b32_e32 v20, v154
	v_add_co_u32_e32 v18, vcc, s3, v12
	s_mov_b32 s3, 0x16000
	s_nop 0
	v_addc_co_u32_e32 v19, vcc, 0, v13, vcc
	v_mov_b32_e32 v18, v155
	s_waitcnt vmcnt(3)
	v_lshlrev_b32_e32 v22, 16, v1
	s_waitcnt vmcnt(2)
	v_lshlrev_b32_e32 v23, 16, v3
	s_waitcnt vmcnt(1)
	v_lshlrev_b32_e32 v20, 16, v20
	s_waitcnt vmcnt(0)
	v_lshlrev_b32_e32 v21, 16, v18
	v_pk_mov_b32 v[16:17], v[16:17], v[20:21] op_sel:[1,0]
	v_pk_mov_b32 v[18:19], v[20:21], v[22:23] op_sel:[1,0]
	v_pk_mov_b32 v[24:25], v[14:15], v[16:17] op_sel:[1,0]
	v_pk_mov_b32 v[26:27], v[16:17], v[18:19] op_sel:[1,0]
	v_pk_mul_f32 v[24:25], v[8:9], v[24:25] op_sel_hi:[0,1]
	v_pk_mul_f32 v[26:27], v[8:9], v[26:27] op_sel_hi:[0,1]
	v_pk_fma_f32 v[14:15], v[4:5], v[14:15], v[24:25] op_sel_hi:[0,1,1]
	v_pk_fma_f32 v[26:27], v[4:5], v[16:17], v[26:27] op_sel_hi:[0,1,1]
	v_pk_fma_f32 v[14:15], v[6:7], v[16:17], v[14:15] op_sel_hi:[0,1,1]
	v_pk_fma_f32 v[16:17], v[6:7], v[18:19], v[26:27] op_sel_hi:[0,1,1]
	v_pk_fma_f32 v[14:15], v[0:1], v[20:21], v[14:15] op_sel_hi:[0,1,1]
	v_pk_fma_f32 v[16:17], v[0:1], v[22:23], v[16:17] op_sel_hi:[0,1,1]
	v_pk_add_f32 v[14:15], v[2:3], v[14:15] op_sel_hi:[0,1]
	v_pk_add_f32 v[16:17], v[2:3], v[16:17] op_sel_hi:[0,1]
	v_cvt_pk_bf16_f32 v14, v14, s0
	v_cvt_pk_bf16_f32 v1, v17, s0
	v_cvt_pk_bf16_f32 v3, v16, s0
	v_cvt_pk_bf16_f32 v15, v15, s0
	ds_write_b16 v11, v14 offset:1728
	ds_write_b16 v11, v15 offset:1872
	ds_write_b16 v11, v3 offset:2016
	ds_write_b16 v11, v1 offset:2160
	v_add_co_u32_e32 v14, vcc, s3, v12
	s_mov_b32 s3, 0x17000
	s_nop 0
	v_addc_co_u32_e32 v15, vcc, 0, v13, vcc
	v_mov_b32_e32 v1, v160
	v_add_co_u32_e32 v14, vcc, s3, v12
	s_mov_b32 s3, 0x14000
	s_nop 0
	v_addc_co_u32_e32 v15, vcc, 0, v13, vcc
	v_mov_b32_e32 v3, v161
	v_add_co_u32_e32 v14, vcc, s3, v12
	s_mov_b32 s3, 0x15000
	s_nop 0
	v_addc_co_u32_e32 v15, vcc, 0, v13, vcc
	v_mov_b32_e32 v16, v158
	v_add_co_u32_e32 v14, vcc, s3, v12
	s_mov_b32 s3, 0x1b000
	s_nop 0
	v_addc_co_u32_e32 v15, vcc, 0, v13, vcc
	v_mov_b32_e32 v14, v159
	s_waitcnt vmcnt(2)
	v_lshlrev_b32_e32 v17, 16, v3
	s_waitcnt vmcnt(0)
; DI u16 f2bf(float f) { return (u16)(pack2(f, 0.f) & 0xffffu); }
; DI float bf2f(u16 h) { return __uint_as_float(((uint32_t)h) << 16); }
; template <bool FINAL>
; DI void lru_item(int ws, PP p, char* shm, int item) {
;     ...
;     for (int t = 0; t < 64; ++t) {
;       float xv = bf2f(up[(long)t * IN0]);
;       float xc = w0 * xm3 + w1 * xm2 + w2 * xm1 + w3 * xv + cb;
;       XC[t * KVS + lane] = f2bf(xc);
;       xm3 = xm2; xm2 = xm1; xm1 = xv;
;     }
	v_lshlrev_b32_e32 v15, 16, v14
	v_lshlrev_b32_e32 v14, 16, v16
	v_lshlrev_b32_e32 v16, 16, v1
	v_pk_mov_b32 v[22:23], v[22:23], v[14:15] op_sel:[1,0]
	v_pk_mov_b32 v[20:21], v[14:15], v[16:17] op_sel:[1,0]
	v_pk_mov_b32 v[24:25], v[18:19], v[22:23] op_sel:[1,0]
	v_pk_mov_b32 v[26:27], v[22:23], v[20:21] op_sel:[1,0]
	v_pk_mul_f32 v[24:25], v[8:9], v[24:25] op_sel_hi:[0,1]
	v_pk_mul_f32 v[26:27], v[8:9], v[26:27] op_sel_hi:[0,1]
	v_pk_fma_f32 v[18:19], v[4:5], v[18:19], v[24:25] op_sel_hi:[0,1,1]
	v_pk_fma_f32 v[26:27], v[4:5], v[22:23], v[26:27] op_sel_hi:[0,1,1]
	v_pk_fma_f32 v[18:19], v[6:7], v[22:23], v[18:19] op_sel_hi:[0,1,1]
	v_pk_fma_f32 v[22:23], v[6:7], v[20:21], v[26:27] op_sel_hi:[0,1,1]
	v_pk_fma_f32 v[14:15], v[0:1], v[14:15], v[18:19] op_sel_hi:[0,1,1]
	v_pk_fma_f32 v[22:23], v[0:1], v[16:17], v[22:23] op_sel_hi:[0,1,1]
	v_pk_add_f32 v[14:15], v[2:3], v[14:15] op_sel_hi:[0,1]
	v_pk_add_f32 v[18:19], v[2:3], v[22:23] op_sel_hi:[0,1]
	v_cvt_pk_bf16_f32 v14, v14, s0
	v_cvt_pk_bf16_f32 v1, v19, s0
	v_cvt_pk_bf16_f32 v3, v18, s0
	v_cvt_pk_bf16_f32 v15, v15, s0
	ds_write_b16 v11, v14 offset:2304
	ds_write_b16 v11, v15 offset:2448
	ds_write_b16 v11, v3 offset:2592
	ds_write_b16 v11, v1 offset:2736
	v_add_co_u32_e32 v14, vcc, s3, v12
	s_mov_b32 s3, 0x1c000
	s_nop 0
	v_addc_co_u32_e32 v15, vcc, 0, v13, vcc
	v_mov_b32_e32 v1, v164
	v_add_co_u32_e32 v14, vcc, s3, v12
	s_mov_b32 s3, 0x19000
	s_nop 0
	v_addc_co_u32_e32 v15, vcc, 0, v13, vcc
	v_mov_b32_e32 v3, v165
	v_add_co_u32_e32 v14, vcc, s3, v12
	s_mov_b32 s3, 0x1a000
	s_nop 0
	v_addc_co_u32_e32 v15, vcc, 0, v13, vcc
	v_mov_b32_e32 v18, v162
	v_add_co_u32_e32 v14, vcc, s3, v12
	s_mov_b32 s3, 0x20000
	s_nop 0
	v_addc_co_u32_e32 v15, vcc, 0, v13, vcc
	v_mov_b32_e32 v14, v163
	s_waitcnt vmcnt(2)
	v_lshlrev_b32_e32 v19, 16, v3
	s_waitcnt vmcnt(0)
	v_lshlrev_b32_e32 v15, 16, v14
	v_lshlrev_b32_e32 v14, 16, v18
	v_lshlrev_b32_e32 v18, 16, v1
	v_pk_mov_b32 v[16:17], v[16:17], v[14:15] op_sel:[1,0]
	v_pk_mov_b32 v[22:23], v[14:15], v[18:19] op_sel:[1,0]
	v_pk_mov_b32 v[24:25], v[20:21], v[16:17] op_sel:[1,0]
	v_pk_mov_b32 v[26:27], v[16:17], v[22:23] op_sel:[1,0]
	v_pk_mul_f32 v[24:25], v[8:9], v[24:25] op_sel_hi:[0,1]
	v_pk_mul_f32 v[26:27], v[8:9], v[26:27] op_sel_hi:[0,1]
	v_pk_fma_f32 v[20:21], v[4:5], v[20:21], v[24:25] op_sel_hi:[0,1,1]
	v_pk_fma_f32 v[26:27], v[4:5], v[16:17], v[26:27] op_sel_hi:[0,1,1]
	v_pk_fma_f32 v[16:17], v[6:7], v[16:17], v[20:21] op_sel_hi:[0,1,1]
	v_pk_fma_f32 v[20:21], v[6:7], v[22:23], v[26:27] op_sel_hi:[0,1,1]
	v_pk_fma_f32 v[14:15], v[0:1], v[14:15], v[16:17] op_sel_hi:[0,1,1]
	v_pk_fma_f32 v[20:21], v[0:1], v[18:19], v[20:21] op_sel_hi:[0,1,1]
	v_pk_add_f32 v[14:15], v[2:3], v[14:15] op_sel_hi:[0,1]
	v_pk_add_f32 v[16:17], v[2:3], v[20:21] op_sel_hi:[0,1]
	v_cvt_pk_bf16_f32 v14, v14, s0
	v_cvt_pk_bf16_f32 v1, v17, s0
	v_cvt_pk_bf16_f32 v3, v16, s0
	v_cvt_pk_bf16_f32 v15, v15, s0
	ds_write_b16 v11, v14 offset:2880
	ds_write_b16 v11, v15 offset:3024
	ds_write_b16 v11, v3 offset:3168
	ds_write_b16 v11, v1 offset:3312
	v_add_co_u32_e32 v14, vcc, s3, v12
	s_mov_b32 s3, 0x21000
	s_nop 0
	v_addc_co_u32_e32 v15, vcc, 0, v13, vcc
	v_mov_b32_e32 v1, v168
	v_add_co_u32_e32 v14, vcc, s3, v12
	s_mov_b32 s3, 0x1e000
	s_nop 0
	v_addc_co_u32_e32 v15, vcc, 0, v13, vcc
	v_mov_b32_e32 v3, v169
	v_add_co_u32_e32 v14, vcc, s3, v12
	s_mov_b32 s3, 0x1f000
	s_nop 0
	v_addc_co_u32_e32 v15, vcc, 0, v13, vcc
	v_mov_b32_e32 v16, v166
	v_add_co_u32_e32 v14, vcc, s3, v12
	s_mov_b32 s3, 0x25000
	s_nop 0
	v_addc_co_u32_e32 v15, vcc, 0, v13, vcc
	v_mov_b32_e32 v14, v167
	s_waitcnt vmcnt(2)
	v_lshlrev_b32_e32 v17, 16, v3
	s_waitcnt vmcnt(1)
	v_lshlrev_b32_e32 v20, 16, v16
	v_lshlrev_b32_e32 v16, 16, v1
	s_waitcnt vmcnt(0)
	v_lshlrev_b32_e32 v21, 16, v14
	v_pk_mov_b32 v[18:19], v[18:19], v[20:21] op_sel:[1,0]
	v_pk_mov_b32 v[14:15], v[20:21], v[16:17] op_sel:[1,0]
	v_pk_mov_b32 v[24:25], v[22:23], v[18:19] op_sel:[1,0]
	v_pk_mov_b32 v[26:27], v[18:19], v[14:15] op_sel:[1,0]
	v_pk_mul_f32 v[24:25], v[8:9], v[24:25] op_sel_hi:[0,1]
	v_pk_mul_f32 v[26:27], v[8:9], v[26:27] op_sel_hi:[0,1]
	v_pk_fma_f32 v[22:23], v[4:5], v[22:23], v[24:25] op_sel_hi:[0,1,1]
	v_pk_fma_f32 v[26:27], v[4:5], v[18:19], v[26:27] op_sel_hi:[0,1,1]
	v_pk_fma_f32 v[18:19], v[6:7], v[18:19], v[22:23] op_sel_hi:[0,1,1]
	v_pk_fma_f32 v[22:23], v[6:7], v[14:15], v[26:27] op_sel_hi:[0,1,1]
	v_pk_fma_f32 v[18:19], v[0:1], v[20:21], v[18:19] op_sel_hi:[0,1,1]
	v_pk_fma_f32 v[22:23], v[0:1], v[16:17], v[22:23] op_sel_hi:[0,1,1]
	v_pk_add_f32 v[18:19], v[2:3], v[18:19] op_sel_hi:[0,1]
	v_pk_add_f32 v[20:21], v[2:3], v[22:23] op_sel_hi:[0,1]
	v_cvt_pk_bf16_f32 v18, v18, s0
	v_cvt_pk_bf16_f32 v1, v21, s0
	v_cvt_pk_bf16_f32 v3, v20, s0
	v_cvt_pk_bf16_f32 v19, v19, s0
	ds_write_b16 v11, v18 offset:3456
	ds_write_b16 v11, v19 offset:3600
	ds_write_b16 v11, v3 offset:3744
	ds_write_b16 v11, v1 offset:3888
	v_add_co_u32_e32 v18, vcc, s3, v12
	s_mov_b32 s3, 0x26000
	s_nop 0
	v_addc_co_u32_e32 v19, vcc, 0, v13, vcc
	v_mov_b32_e32 v1, v172
	v_add_co_u32_e32 v18, vcc, s3, v12
	s_mov_b32 s3, 0x23000
	s_nop 0
	v_addc_co_u32_e32 v19, vcc, 0, v13, vcc
	v_mov_b32_e32 v3, v173
	v_add_co_u32_e32 v18, vcc, s3, v12
	s_mov_b32 s3, 0x24000
	s_nop 0
	v_addc_co_u32_e32 v19, vcc, 0, v13, vcc
	v_mov_b32_e32 v20, v170
	v_add_co_u32_e32 v18, vcc, s3, v12
	s_mov_b32 s3, 0x2a000
	s_nop 0
	v_addc_co_u32_e32 v19, vcc, 0, v13, vcc
	v_mov_b32_e32 v18, v171
	s_waitcnt vmcnt(2)
	v_lshlrev_b32_e32 v21, 16, v3
	s_waitcnt vmcnt(1)
	v_lshlrev_b32_e32 v22, 16, v20
	v_lshlrev_b32_e32 v20, 16, v1
	s_waitcnt vmcnt(0)
; DI u16 f2bf(float f) { return (u16)(pack2(f, 0.f) & 0xffffu); }
; DI float bf2f(u16 h) { return __uint_as_float(((uint32_t)h) << 16); }
; template <bool FINAL>
; DI void lru_item(int ws, PP p, char* shm, int item) {
;     ...
;     for (int t = 0; t < 64; ++t) {
;       float xv = bf2f(up[(long)t * IN0]);
;       float xc = w0 * xm3 + w1 * xm2 + w2 * xm1 + w3 * xv + cb;
;       XC[t * KVS + lane] = f2bf(xc);
;       xm3 = xm2; xm2 = xm1; xm1 = xv;
;     }
	v_lshlrev_b32_e32 v23, 16, v18
	v_pk_mov_b32 v[16:17], v[16:17], v[22:23] op_sel:[1,0]
	v_pk_mov_b32 v[18:19], v[22:23], v[20:21] op_sel:[1,0]
	v_pk_mov_b32 v[24:25], v[14:15], v[16:17] op_sel:[1,0]
	v_pk_mov_b32 v[26:27], v[16:17], v[18:19] op_sel:[1,0]
	v_pk_mul_f32 v[24:25], v[8:9], v[24:25] op_sel_hi:[0,1]
	v_pk_mul_f32 v[26:27], v[8:9], v[26:27] op_sel_hi:[0,1]
	v_pk_fma_f32 v[14:15], v[4:5], v[14:15], v[24:25] op_sel_hi:[0,1,1]
	v_pk_fma_f32 v[26:27], v[4:5], v[16:17], v[26:27] op_sel_hi:[0,1,1]
	v_pk_fma_f32 v[14:15], v[6:7], v[16:17], v[14:15] op_sel_hi:[0,1,1]
	v_pk_fma_f32 v[16:17], v[6:7], v[18:19], v[26:27] op_sel_hi:[0,1,1]
	v_pk_fma_f32 v[14:15], v[0:1], v[22:23], v[14:15] op_sel_hi:[0,1,1]
	v_pk_fma_f32 v[16:17], v[0:1], v[20:21], v[16:17] op_sel_hi:[0,1,1]
	v_pk_add_f32 v[14:15], v[2:3], v[14:15] op_sel_hi:[0,1]
	v_pk_add_f32 v[16:17], v[2:3], v[16:17] op_sel_hi:[0,1]
	v_cvt_pk_bf16_f32 v14, v14, s0
	v_cvt_pk_bf16_f32 v1, v17, s0
	v_cvt_pk_bf16_f32 v3, v16, s0
	v_cvt_pk_bf16_f32 v15, v15, s0
	ds_write_b16 v11, v14 offset:4032
	ds_write_b16 v11, v15 offset:4176
	ds_write_b16 v11, v3 offset:4320
	ds_write_b16 v11, v1 offset:4464
	v_add_co_u32_e32 v14, vcc, s3, v12
	s_mov_b32 s3, 0x2b000
	s_nop 0
	v_addc_co_u32_e32 v15, vcc, 0, v13, vcc
	s_mov_b32 s98, 0x1400
	s_mov_b32 s99, 0
	s_mov_b32 s100, 0x28000
	s_mov_b32 s101, 0
	v_lshl_add_u64 v[228:229], v[12:13], 0, s[100:101]
	global_load_ushort v174, v[228:229], off
	v_lshl_add_u64 v[228:229], v[228:229], 0, s[98:99]
	global_load_ushort v175, v[228:229], off
	v_lshl_add_u64 v[228:229], v[228:229], 0, s[98:99]
	global_load_ushort v176, v[228:229], off
	v_lshl_add_u64 v[228:229], v[228:229], 0, s[98:99]
	global_load_ushort v177, v[228:229], off
	v_lshl_add_u64 v[228:229], v[228:229], 0, s[98:99]
	global_load_ushort v178, v[228:229], off
	v_lshl_add_u64 v[228:229], v[228:229], 0, s[98:99]
	global_load_ushort v179, v[228:229], off
	v_lshl_add_u64 v[228:229], v[228:229], 0, s[98:99]
	global_load_ushort v180, v[228:229], off
	v_lshl_add_u64 v[228:229], v[228:229], 0, s[98:99]
	global_load_ushort v181, v[228:229], off
	v_lshl_add_u64 v[228:229], v[228:229], 0, s[98:99]
	global_load_ushort v182, v[228:229], off
	v_lshl_add_u64 v[228:229], v[228:229], 0, s[98:99]
	global_load_ushort v183, v[228:229], off
	v_lshl_add_u64 v[228:229], v[228:229], 0, s[98:99]
	global_load_ushort v184, v[228:229], off
	v_lshl_add_u64 v[228:229], v[228:229], 0, s[98:99]
	global_load_ushort v185, v[228:229], off
	v_lshl_add_u64 v[228:229], v[228:229], 0, s[98:99]
	global_load_ushort v186, v[228:229], off
	v_lshl_add_u64 v[228:229], v[228:229], 0, s[98:99]
	global_load_ushort v187, v[228:229], off
	v_lshl_add_u64 v[228:229], v[228:229], 0, s[98:99]
	global_load_ushort v188, v[228:229], off
	v_lshl_add_u64 v[228:229], v[228:229], 0, s[98:99]
	global_load_ushort v189, v[228:229], off
	v_lshl_add_u64 v[228:229], v[228:229], 0, s[98:99]
	global_load_ushort v190, v[228:229], off
	v_lshl_add_u64 v[228:229], v[228:229], 0, s[98:99]
	global_load_ushort v191, v[228:229], off
	v_lshl_add_u64 v[228:229], v[228:229], 0, s[98:99]
	global_load_ushort v192, v[228:229], off
	v_lshl_add_u64 v[228:229], v[228:229], 0, s[98:99]
	global_load_ushort v193, v[228:229], off
	v_lshl_add_u64 v[228:229], v[228:229], 0, s[98:99]
	global_load_ushort v194, v[228:229], off
	v_lshl_add_u64 v[228:229], v[228:229], 0, s[98:99]
	global_load_ushort v196, v[228:229], off
	v_lshl_add_u64 v[228:229], v[228:229], 0, s[98:99]
	global_load_ushort v197, v[228:229], off
	v_lshl_add_u64 v[228:229], v[228:229], 0, s[98:99]
	global_load_ushort v198, v[228:229], off
	v_lshl_add_u64 v[228:229], v[228:229], 0, s[98:99]
	global_load_ushort v199, v[228:229], off
	v_lshl_add_u64 v[228:229], v[228:229], 0, s[98:99]
	global_load_ushort v200, v[228:229], off
	v_lshl_add_u64 v[228:229], v[228:229], 0, s[98:99]
	global_load_ushort v201, v[228:229], off
	v_lshl_add_u64 v[228:229], v[228:229], 0, s[98:99]
	global_load_ushort v202, v[228:229], off
	v_lshl_add_u64 v[228:229], v[228:229], 0, s[98:99]
	global_load_ushort v203, v[228:229], off
	v_lshl_add_u64 v[228:229], v[228:229], 0, s[98:99]
	global_load_ushort v204, v[228:229], off
	v_lshl_add_u64 v[228:229], v[228:229], 0, s[98:99]
	global_load_ushort v205, v[228:229], off
	v_lshl_add_u64 v[228:229], v[228:229], 0, s[98:99]
	global_load_ushort v206, v[228:229], off
	s_waitcnt vmcnt(0)
	v_mov_b32_e32 v1, v176
	v_add_co_u32_e32 v14, vcc, s3, v12
	s_mov_b32 s3, 0x28000
	s_nop 0
	v_addc_co_u32_e32 v15, vcc, 0, v13, vcc
	v_mov_b32_e32 v3, v177
	v_add_co_u32_e32 v14, vcc, s3, v12
	s_mov_b32 s3, 0x29000
	s_nop 0
	v_addc_co_u32_e32 v15, vcc, 0, v13, vcc
	v_mov_b32_e32 v16, v174
	v_add_co_u32_e32 v14, vcc, s3, v12
	s_mov_b32 s3, 0x2f000
	s_nop 0
	v_addc_co_u32_e32 v15, vcc, 0, v13, vcc
	v_mov_b32_e32 v14, v175
	s_waitcnt vmcnt(2)
	v_lshlrev_b32_e32 v17, 16, v3
	s_waitcnt vmcnt(0)
; DI u16 f2bf(float f) { return (u16)(pack2(f, 0.f) & 0xffffu); }
; DI float bf2f(u16 h) { return __uint_as_float(((uint32_t)h) << 16); }
; template <bool FINAL>
; DI void lru_item(int ws, PP p, char* shm, int item) {
;     ...
;     for (int t = 0; t < 64; ++t) {
;       float xv = bf2f(up[(long)t * IN0]);
;       float xc = w0 * xm3 + w1 * xm2 + w2 * xm1 + w3 * xv + cb;
;       XC[t * KVS + lane] = f2bf(xc);
;       xm3 = xm2; xm2 = xm1; xm1 = xv;
;     }
;   }
	v_lshlrev_b32_e32 v15, 16, v14
	v_lshlrev_b32_e32 v14, 16, v16
	v_lshlrev_b32_e32 v16, 16, v1
	v_pk_mov_b32 v[20:21], v[20:21], v[14:15] op_sel:[1,0]
	v_pk_mov_b32 v[22:23], v[14:15], v[16:17] op_sel:[1,0]
	v_pk_mov_b32 v[24:25], v[18:19], v[20:21] op_sel:[1,0]
	v_pk_mov_b32 v[26:27], v[20:21], v[22:23] op_sel:[1,0]
	v_pk_mul_f32 v[24:25], v[8:9], v[24:25] op_sel_hi:[0,1]
	v_pk_mul_f32 v[26:27], v[8:9], v[26:27] op_sel_hi:[0,1]
	v_pk_fma_f32 v[18:19], v[4:5], v[18:19], v[24:25] op_sel_hi:[0,1,1]
	v_pk_fma_f32 v[26:27], v[4:5], v[20:21], v[26:27] op_sel_hi:[0,1,1]
	v_pk_fma_f32 v[18:19], v[6:7], v[20:21], v[18:19] op_sel_hi:[0,1,1]
	v_pk_fma_f32 v[20:21], v[6:7], v[22:23], v[26:27] op_sel_hi:[0,1,1]
	v_pk_fma_f32 v[14:15], v[0:1], v[14:15], v[18:19] op_sel_hi:[0,1,1]
	v_pk_fma_f32 v[20:21], v[0:1], v[16:17], v[20:21] op_sel_hi:[0,1,1]
	v_pk_add_f32 v[14:15], v[2:3], v[14:15] op_sel_hi:[0,1]
	v_pk_add_f32 v[18:19], v[2:3], v[20:21] op_sel_hi:[0,1]
	v_cvt_pk_bf16_f32 v14, v14, s0
	v_cvt_pk_bf16_f32 v1, v19, s0
	v_cvt_pk_bf16_f32 v3, v18, s0
	v_cvt_pk_bf16_f32 v15, v15, s0
	ds_write_b16 v11, v14 offset:4608
	ds_write_b16 v11, v15 offset:4752
	ds_write_b16 v11, v3 offset:4896
	ds_write_b16 v11, v1 offset:5040
	v_add_co_u32_e32 v14, vcc, s3, v12
	s_mov_b32 s3, 0x30000
	s_nop 0
	v_addc_co_u32_e32 v15, vcc, 0, v13, vcc
	v_mov_b32_e32 v1, v180
	v_add_co_u32_e32 v14, vcc, s3, v12
	s_mov_b32 s3, 0x2d000
	s_nop 0
	v_addc_co_u32_e32 v15, vcc, 0, v13, vcc
	v_mov_b32_e32 v3, v181
	v_add_co_u32_e32 v14, vcc, s3, v12
	s_lshl_b32 s3, s6, 19
	s_nop 0
	v_addc_co_u32_e32 v15, vcc, 0, v13, vcc
	v_mov_b32_e32 v18, v178
	v_add_co_u32_e32 v14, vcc, s53, v12
	s_cmp_gt_u32 s1, 6
	s_nop 0
	v_addc_co_u32_e32 v15, vcc, 0, v13, vcc
	v_mov_b32_e32 v14, v179
	s_cselect_b64 s[40:41], -1, 0
	s_and_b32 s90, s0, -8
	s_cmp_lg_u32 s89, 0
	s_cselect_b64 s[42:43], -1, 0
	s_waitcnt vmcnt(3)
	v_lshlrev_b32_e32 v24, 16, v1
	s_waitcnt vmcnt(2)
	v_lshlrev_b32_e32 v25, 16, v3
	s_waitcnt vmcnt(0)
	v_lshlrev_b32_e32 v15, 16, v14
	v_lshlrev_b32_e32 v14, 16, v18
	v_pk_mov_b32 v[16:17], v[16:17], v[14:15] op_sel:[1,0]
	v_pk_mov_b32 v[26:27], v[14:15], v[24:25] op_sel:[1,0]
	v_pk_mov_b32 v[18:19], v[22:23], v[16:17] op_sel:[1,0]
	v_pk_mov_b32 v[20:21], v[16:17], v[26:27] op_sel:[1,0]
	v_pk_mul_f32 v[18:19], v[8:9], v[18:19] op_sel_hi:[0,1]
	v_pk_mul_f32 v[20:21], v[8:9], v[20:21] op_sel_hi:[0,1]
	v_pk_fma_f32 v[18:19], v[4:5], v[22:23], v[18:19] op_sel_hi:[0,1,1]
	v_pk_fma_f32 v[20:21], v[4:5], v[16:17], v[20:21] op_sel_hi:[0,1,1]
	v_pk_fma_f32 v[16:17], v[6:7], v[16:17], v[18:19] op_sel_hi:[0,1,1]
	v_pk_fma_f32 v[18:19], v[6:7], v[26:27], v[20:21] op_sel_hi:[0,1,1]
	v_pk_fma_f32 v[14:15], v[0:1], v[14:15], v[16:17] op_sel_hi:[0,1,1]
	v_pk_fma_f32 v[18:19], v[0:1], v[24:25], v[18:19] op_sel_hi:[0,1,1]
	v_pk_add_f32 v[14:15], v[2:3], v[14:15] op_sel_hi:[0,1]
	v_pk_add_f32 v[16:17], v[2:3], v[18:19] op_sel_hi:[0,1]
	v_cvt_pk_bf16_f32 v14, v14, s0
	v_cvt_pk_bf16_f32 v1, v17, s0
	v_cvt_pk_bf16_f32 v3, v16, s0
	v_cvt_pk_bf16_f32 v15, v15, s0
	ds_write_b16 v11, v14 offset:5184
	ds_write_b16 v11, v15 offset:5328
	ds_write_b16 v11, v3 offset:5472
	ds_write_b16 v11, v1 offset:5616
	v_add_co_u32_e32 v14, vcc, s54, v12
	s_nop 1
	v_addc_co_u32_e32 v15, vcc, 0, v13, vcc
	v_mov_b32_e32 v1, v184
	v_add_co_u32_e32 v14, vcc, s55, v12
	s_waitcnt vmcnt(0)
	v_lshlrev_b32_e32 v20, 16, v1
	v_addc_co_u32_e32 v15, vcc, 0, v13, vcc
	v_mov_b32_e32 v3, v185
	v_add_co_u32_e32 v14, vcc, s56, v12
	s_waitcnt vmcnt(0)
	v_lshlrev_b32_e32 v21, 16, v3
	v_addc_co_u32_e32 v15, vcc, 0, v13, vcc
	v_mov_b32_e32 v16, v182
	v_add_co_u32_e32 v14, vcc, s57, v12
	s_nop 1
	v_addc_co_u32_e32 v15, vcc, 0, v13, vcc
	v_mov_b32_e32 v14, v183
	s_waitcnt vmcnt(0)
	v_lshlrev_b32_e32 v15, 16, v14
	v_lshlrev_b32_e32 v14, 16, v16
	v_pk_mov_b32 v[16:17], v[24:25], v[14:15] op_sel:[1,0]
	v_pk_mov_b32 v[18:19], v[14:15], v[20:21] op_sel:[1,0]
	v_pk_mov_b32 v[22:23], v[26:27], v[16:17] op_sel:[1,0]
	v_pk_mov_b32 v[24:25], v[16:17], v[18:19] op_sel:[1,0]
	v_pk_mul_f32 v[22:23], v[8:9], v[22:23] op_sel_hi:[0,1]
	v_pk_mul_f32 v[24:25], v[8:9], v[24:25] op_sel_hi:[0,1]
	v_pk_fma_f32 v[22:23], v[4:5], v[26:27], v[22:23] op_sel_hi:[0,1,1]
	v_pk_fma_f32 v[24:25], v[4:5], v[16:17], v[24:25] op_sel_hi:[0,1,1]
	v_pk_fma_f32 v[16:17], v[6:7], v[16:17], v[22:23] op_sel_hi:[0,1,1]
	v_pk_fma_f32 v[22:23], v[6:7], v[18:19], v[24:25] op_sel_hi:[0,1,1]
	v_pk_fma_f32 v[14:15], v[0:1], v[14:15], v[16:17] op_sel_hi:[0,1,1]
	v_pk_fma_f32 v[22:23], v[0:1], v[20:21], v[22:23] op_sel_hi:[0,1,1]
	v_pk_add_f32 v[14:15], v[2:3], v[14:15] op_sel_hi:[0,1]
	v_pk_add_f32 v[16:17], v[2:3], v[22:23] op_sel_hi:[0,1]
	v_cvt_pk_bf16_f32 v14, v14, s0
	v_cvt_pk_bf16_f32 v1, v17, s0
	v_cvt_pk_bf16_f32 v3, v16, s0
	v_cvt_pk_bf16_f32 v15, v15, s0
	ds_write_b16 v11, v14 offset:5760
	ds_write_b16 v11, v15 offset:5904
	ds_write_b16 v11, v3 offset:6048
	ds_write_b16 v11, v1 offset:6192
	v_add_co_u32_e32 v14, vcc, s58, v12
	s_nop 1
	v_addc_co_u32_e32 v15, vcc, 0, v13, vcc
	v_mov_b32_e32 v1, v188
	v_add_co_u32_e32 v14, vcc, s59, v12
	s_nop 1
	v_addc_co_u32_e32 v15, vcc, 0, v13, vcc
	v_mov_b32_e32 v3, v189
	v_add_co_u32_e32 v14, vcc, s60, v12
	s_waitcnt vmcnt(0)
	v_lshlrev_b32_e32 v17, 16, v3
	v_addc_co_u32_e32 v15, vcc, 0, v13, vcc
	v_mov_b32_e32 v16, v186
	v_add_co_u32_e32 v14, vcc, s61, v12
	s_waitcnt vmcnt(0)
	v_lshlrev_b32_e32 v22, 16, v16
	v_addc_co_u32_e32 v15, vcc, 0, v13, vcc
	v_mov_b32_e32 v14, v187
	v_lshlrev_b32_e32 v16, 16, v1
	s_waitcnt vmcnt(0)
; DI u16 f2bf(float f) { return (u16)(pack2(f, 0.f) & 0xffffu); }
; DI float bf2f(u16 h) { return __uint_as_float(((uint32_t)h) << 16); }
; template <bool FINAL>
; DI void lru_item(int ws, PP p, char* shm, int item) {
;     ...
;     for (int t = 0; t < 64; ++t) {
;       float xv = bf2f(up[(long)t * IN0]);
;       float xc = w0 * xm3 + w1 * xm2 + w2 * xm1 + w3 * xv + cb;
;       XC[t * KVS + lane] = f2bf(xc);
;       xm3 = xm2; xm2 = xm1; xm1 = xv;
;     }
	v_lshlrev_b32_e32 v23, 16, v14
	v_pk_mov_b32 v[20:21], v[20:21], v[22:23] op_sel:[1,0]
	v_pk_mov_b32 v[14:15], v[22:23], v[16:17] op_sel:[1,0]
	v_pk_mov_b32 v[24:25], v[18:19], v[20:21] op_sel:[1,0]
	v_pk_mov_b32 v[26:27], v[20:21], v[14:15] op_sel:[1,0]
	v_pk_mul_f32 v[24:25], v[8:9], v[24:25] op_sel_hi:[0,1]
	v_pk_mul_f32 v[26:27], v[8:9], v[26:27] op_sel_hi:[0,1]
	v_pk_fma_f32 v[18:19], v[4:5], v[18:19], v[24:25] op_sel_hi:[0,1,1]
	v_pk_fma_f32 v[26:27], v[4:5], v[20:21], v[26:27] op_sel_hi:[0,1,1]
	v_pk_fma_f32 v[18:19], v[6:7], v[20:21], v[18:19] op_sel_hi:[0,1,1]
	v_pk_fma_f32 v[20:21], v[6:7], v[14:15], v[26:27] op_sel_hi:[0,1,1]
	v_pk_fma_f32 v[18:19], v[0:1], v[22:23], v[18:19] op_sel_hi:[0,1,1]
	v_pk_fma_f32 v[20:21], v[0:1], v[16:17], v[20:21] op_sel_hi:[0,1,1]
	v_pk_add_f32 v[18:19], v[2:3], v[18:19] op_sel_hi:[0,1]
	v_pk_add_f32 v[20:21], v[2:3], v[20:21] op_sel_hi:[0,1]
	v_cvt_pk_bf16_f32 v18, v18, s0
	v_cvt_pk_bf16_f32 v1, v21, s0
	v_cvt_pk_bf16_f32 v3, v20, s0
	v_cvt_pk_bf16_f32 v19, v19, s0
	ds_write_b16 v11, v18 offset:6336
	ds_write_b16 v11, v19 offset:6480
	ds_write_b16 v11, v3 offset:6624
	ds_write_b16 v11, v1 offset:6768
	v_add_co_u32_e32 v18, vcc, s62, v12
	s_nop 1
	v_addc_co_u32_e32 v19, vcc, 0, v13, vcc
	v_mov_b32_e32 v1, v192
	v_add_co_u32_e32 v18, vcc, s63, v12
	s_nop 1
	v_addc_co_u32_e32 v19, vcc, 0, v13, vcc
	v_mov_b32_e32 v3, v193
	v_add_co_u32_e32 v18, vcc, s64, v12
	s_waitcnt vmcnt(0)
	v_lshlrev_b32_e32 v21, 16, v3
	v_addc_co_u32_e32 v19, vcc, 0, v13, vcc
	v_mov_b32_e32 v20, v190
	v_add_co_u32_e32 v18, vcc, s65, v12
	s_nop 1
	v_addc_co_u32_e32 v19, vcc, 0, v13, vcc
	v_mov_b32_e32 v18, v191
	s_waitcnt vmcnt(0)
	v_lshlrev_b32_e32 v19, 16, v18
	v_lshlrev_b32_e32 v18, 16, v20
	v_lshlrev_b32_e32 v20, 16, v1
	v_pk_mov_b32 v[16:17], v[16:17], v[18:19] op_sel:[1,0]
	v_pk_mov_b32 v[22:23], v[18:19], v[20:21] op_sel:[1,0]
	v_pk_mov_b32 v[24:25], v[14:15], v[16:17] op_sel:[1,0]
	v_pk_mov_b32 v[26:27], v[16:17], v[22:23] op_sel:[1,0]
	v_pk_mul_f32 v[24:25], v[8:9], v[24:25] op_sel_hi:[0,1]
	v_pk_mul_f32 v[26:27], v[8:9], v[26:27] op_sel_hi:[0,1]
	v_pk_fma_f32 v[14:15], v[4:5], v[14:15], v[24:25] op_sel_hi:[0,1,1]
	v_pk_fma_f32 v[26:27], v[4:5], v[16:17], v[26:27] op_sel_hi:[0,1,1]
	v_pk_fma_f32 v[14:15], v[6:7], v[16:17], v[14:15] op_sel_hi:[0,1,1]
	v_pk_fma_f32 v[16:17], v[6:7], v[22:23], v[26:27] op_sel_hi:[0,1,1]
	v_pk_fma_f32 v[14:15], v[0:1], v[18:19], v[14:15] op_sel_hi:[0,1,1]
	v_pk_fma_f32 v[16:17], v[0:1], v[20:21], v[16:17] op_sel_hi:[0,1,1]
	v_pk_add_f32 v[14:15], v[2:3], v[14:15] op_sel_hi:[0,1]
	v_pk_add_f32 v[16:17], v[2:3], v[16:17] op_sel_hi:[0,1]
	v_cvt_pk_bf16_f32 v14, v14, s0
	v_cvt_pk_bf16_f32 v1, v17, s0
	v_cvt_pk_bf16_f32 v3, v16, s0
	v_cvt_pk_bf16_f32 v15, v15, s0
	ds_write_b16 v11, v14 offset:6912
	ds_write_b16 v11, v15 offset:7056
	ds_write_b16 v11, v3 offset:7200
	ds_write_b16 v11, v1 offset:7344
	v_add_co_u32_e32 v14, vcc, s66, v12
	s_nop 1
	v_addc_co_u32_e32 v15, vcc, 0, v13, vcc
	v_mov_b32_e32 v1, v197
	v_add_co_u32_e32 v14, vcc, s67, v12
	s_waitcnt vmcnt(0)
	v_lshlrev_b32_e32 v18, 16, v1
	v_addc_co_u32_e32 v15, vcc, 0, v13, vcc
	v_mov_b32_e32 v3, v198
	v_add_co_u32_e32 v14, vcc, s68, v12
	s_waitcnt vmcnt(0)
	v_lshlrev_b32_e32 v19, 16, v3
	v_addc_co_u32_e32 v15, vcc, 0, v13, vcc
	v_mov_b32_e32 v16, v194
	v_add_co_u32_e32 v14, vcc, s69, v12
	s_nop 1
	v_addc_co_u32_e32 v15, vcc, 0, v13, vcc
	v_mov_b32_e32 v14, v196
	s_waitcnt vmcnt(0)
	v_lshlrev_b32_e32 v15, 16, v14
	v_lshlrev_b32_e32 v14, 16, v16
	v_pk_mov_b32 v[16:17], v[20:21], v[14:15] op_sel:[1,0]
	v_pk_mov_b32 v[24:25], v[14:15], v[18:19] op_sel:[1,0]
	v_pk_mov_b32 v[20:21], v[22:23], v[16:17] op_sel:[1,0]
	v_pk_mov_b32 v[26:27], v[16:17], v[24:25] op_sel:[1,0]
	v_pk_mul_f32 v[20:21], v[8:9], v[20:21] op_sel_hi:[0,1]
	v_pk_mul_f32 v[26:27], v[8:9], v[26:27] op_sel_hi:[0,1]
	v_pk_fma_f32 v[20:21], v[4:5], v[22:23], v[20:21] op_sel_hi:[0,1,1]
	v_pk_fma_f32 v[26:27], v[4:5], v[16:17], v[26:27] op_sel_hi:[0,1,1]
	v_pk_fma_f32 v[16:17], v[6:7], v[16:17], v[20:21] op_sel_hi:[0,1,1]
	v_pk_fma_f32 v[20:21], v[6:7], v[24:25], v[26:27] op_sel_hi:[0,1,1]
	v_pk_fma_f32 v[14:15], v[0:1], v[14:15], v[16:17] op_sel_hi:[0,1,1]
	v_pk_fma_f32 v[20:21], v[0:1], v[18:19], v[20:21] op_sel_hi:[0,1,1]
	v_pk_add_f32 v[14:15], v[2:3], v[14:15] op_sel_hi:[0,1]
	v_pk_add_f32 v[16:17], v[2:3], v[20:21] op_sel_hi:[0,1]
	v_cvt_pk_bf16_f32 v14, v14, s0
	v_cvt_pk_bf16_f32 v1, v17, s0
	v_cvt_pk_bf16_f32 v3, v16, s0
	v_cvt_pk_bf16_f32 v15, v15, s0
	ds_write_b16 v11, v14 offset:7488
	ds_write_b16 v11, v15 offset:7632
	ds_write_b16 v11, v3 offset:7776
	ds_write_b16 v11, v1 offset:7920
	v_add_co_u32_e32 v14, vcc, s70, v12
	s_nop 1
	v_addc_co_u32_e32 v15, vcc, 0, v13, vcc
	v_mov_b32_e32 v1, v201
	v_add_co_u32_e32 v14, vcc, s71, v12
	s_nop 1
	v_addc_co_u32_e32 v15, vcc, 0, v13, vcc
	v_mov_b32_e32 v3, v202
	v_add_co_u32_e32 v14, vcc, s72, v12
	s_waitcnt vmcnt(0)
; DI u16 f2bf(float f) { return (u16)(pack2(f, 0.f) & 0xffffu); }
; DI float bf2f(u16 h) { return __uint_as_float(((uint32_t)h) << 16); }
; template <bool FINAL>
; DI void lru_item(int ws, PP p, char* shm, int item) {
;     ...
;     for (int t = 0; t < 64; ++t) {
;       float xv = bf2f(up[(long)t * IN0]);
;       float xc = w0 * xm3 + w1 * xm2 + w2 * xm1 + w3 * xv + cb;
;       XC[t * KVS + lane] = f2bf(xc);
;       xm3 = xm2; xm2 = xm1; xm1 = xv;
;     }
;   }
;   __syncthreads();
;   const u16* wat = p->wat + (long)wid * 4096;
;   const u16* wxt = p->wat + (long)(8 + wid) * 4096;
	v_lshlrev_b32_e32 v17, 16, v3
	v_addc_co_u32_e32 v15, vcc, 0, v13, vcc
	v_mov_b32_e32 v16, v199
	v_add_co_u32_e32 v14, vcc, s73, v12
	s_waitcnt vmcnt(0)
	v_lshlrev_b32_e32 v20, 16, v16
	v_addc_co_u32_e32 v15, vcc, 0, v13, vcc
	v_mov_b32_e32 v14, v200
	v_lshlrev_b32_e32 v16, 16, v1
	s_waitcnt vmcnt(0)
	v_lshlrev_b32_e32 v21, 16, v14
	v_pk_mov_b32 v[18:19], v[18:19], v[20:21] op_sel:[1,0]
	v_pk_mov_b32 v[14:15], v[20:21], v[16:17] op_sel:[1,0]
	v_pk_mov_b32 v[22:23], v[24:25], v[18:19] op_sel:[1,0]
	v_pk_mov_b32 v[26:27], v[18:19], v[14:15] op_sel:[1,0]
	v_pk_mul_f32 v[22:23], v[8:9], v[22:23] op_sel_hi:[0,1]
	v_pk_mul_f32 v[26:27], v[8:9], v[26:27] op_sel_hi:[0,1]
	v_pk_fma_f32 v[22:23], v[4:5], v[24:25], v[22:23] op_sel_hi:[0,1,1]
	v_pk_fma_f32 v[26:27], v[4:5], v[18:19], v[26:27] op_sel_hi:[0,1,1]
	v_pk_fma_f32 v[18:19], v[6:7], v[18:19], v[22:23] op_sel_hi:[0,1,1]
	v_pk_fma_f32 v[22:23], v[6:7], v[14:15], v[26:27] op_sel_hi:[0,1,1]
	v_pk_fma_f32 v[18:19], v[0:1], v[20:21], v[18:19] op_sel_hi:[0,1,1]
	v_pk_fma_f32 v[22:23], v[0:1], v[16:17], v[22:23] op_sel_hi:[0,1,1]
	v_pk_add_f32 v[18:19], v[2:3], v[18:19] op_sel_hi:[0,1]
	v_pk_add_f32 v[20:21], v[2:3], v[22:23] op_sel_hi:[0,1]
	v_cvt_pk_bf16_f32 v18, v18, s0
	v_cvt_pk_bf16_f32 v1, v21, s0
	v_cvt_pk_bf16_f32 v3, v20, s0
	v_cvt_pk_bf16_f32 v19, v19, s0
	ds_write_b16 v11, v18 offset:8064
	ds_write_b16 v11, v19 offset:8208
	ds_write_b16 v11, v3 offset:8352
	ds_write_b16 v11, v1 offset:8496
	v_add_co_u32_e32 v18, vcc, s80, v12
	s_nop 1
	v_addc_co_u32_e32 v19, vcc, 0, v13, vcc
	v_mov_b32_e32 v1, v203
	v_add_co_u32_e32 v18, vcc, s81, v12
	s_nop 1
	v_addc_co_u32_e32 v19, vcc, 0, v13, vcc
	v_mov_b32_e32 v3, v204
	v_add_co_u32_e32 v18, vcc, s82, v12
	s_nop 1
	v_addc_co_u32_e32 v19, vcc, 0, v13, vcc
	v_add_co_u32_e32 v12, vcc, s83, v12
	v_mov_b32_e32 v18, v205
	s_nop 0
	v_addc_co_u32_e32 v13, vcc, 0, v13, vcc
	v_mov_b32_e32 v12, v206
	s_waitcnt vmcnt(2)
	v_lshlrev_b32_e32 v19, 16, v3
	s_waitcnt vmcnt(0)
	v_lshlrev_b32_e32 v13, 16, v12
	v_lshlrev_b32_e32 v12, 16, v18
	v_lshlrev_b32_e32 v18, 16, v1
	v_pk_mov_b32 v[16:17], v[16:17], v[18:19] op_sel:[1,0]
	v_pk_mov_b32 v[20:21], v[18:19], v[12:13] op_sel:[1,0]
	v_pk_mov_b32 v[22:23], v[14:15], v[16:17] op_sel:[1,0]
	v_pk_mov_b32 v[24:25], v[16:17], v[20:21] op_sel:[1,0]
	v_pk_mul_f32 v[22:23], v[8:9], v[22:23] op_sel_hi:[0,1]
	v_pk_mul_f32 v[24:25], v[8:9], v[24:25] op_sel_hi:[0,1]
	v_pk_fma_f32 v[24:25], v[4:5], v[16:17], v[24:25] op_sel_hi:[0,1,1]
	v_pk_fma_f32 v[14:15], v[4:5], v[14:15], v[22:23] op_sel_hi:[0,1,1]
	v_pk_fma_f32 v[14:15], v[6:7], v[16:17], v[14:15] op_sel_hi:[0,1,1]
	v_pk_fma_f32 v[16:17], v[6:7], v[20:21], v[24:25] op_sel_hi:[0,1,1]
	v_pk_fma_f32 v[12:13], v[0:1], v[12:13], v[16:17] op_sel_hi:[0,1,1]
	v_pk_fma_f32 v[0:1], v[0:1], v[18:19], v[14:15] op_sel_hi:[0,1,1]
	v_pk_add_f32 v[0:1], v[2:3], v[0:1] op_sel_hi:[0,1]
	v_pk_add_f32 v[2:3], v[2:3], v[12:13] op_sel_hi:[0,1]
	v_cvt_pk_bf16_f32 v0, v0, s0
	v_cvt_pk_bf16_f32 v3, v3, s0
	v_cvt_pk_bf16_f32 v2, v2, s0
	v_cvt_pk_bf16_f32 v1, v1, s0
	ds_write_b16 v11, v0 offset:8640
	ds_write_b16 v11, v1 offset:8784
	ds_write_b16 v11, v2 offset:8928
	ds_write_b16 v11, v3 offset:9072
	s_waitcnt lgkmcnt(0)
	s_barrier
	s_load_dwordx2 s[4:5], s[16:17], 0xf0
	v_ashrrev_i32_e32 v11, 31, v10
	v_lshlrev_b64 v[0:1], 13, v[10:11]
	s_load_dwordx2 s[38:39], s[16:17], 0x58
	s_load_dwordx4 s[12:15], s[16:17], 0x68
	v_lshlrev_b32_e32 v2, 6, v84
	s_waitcnt lgkmcnt(0)
	v_lshl_add_u64 v[0:1], s[4:5], 0, v[0:1]
	s_load_dwordx2 s[4:5], s[16:17], 0x118
	v_lshl_add_u64 v[66:67], v[0:1], 0, v[64:65]
	v_or_b32_e32 v0, v9, v64
	v_mul_u32_u24_e32 v1, 0x90, v84
	v_lshl_add_u64 v[68:69], v[66:67], 0, s[24:25]
	s_waitcnt lgkmcnt(0)
	s_add_u32 s0, s4, s3
	s_addc_u32 s1, s5, 0
	s_add_u32 s44, s0, 0x7004
	s_addc_u32 s45, s1, 0
	s_add_u32 s91, s0, 4
	s_addc_u32 s92, s1, 0
	v_lshlrev_b32_e32 v88, 1, v2
	v_add_u32_e32 v89, v0, v1
	s_branch .LBB0_675
